# grid barrier: buffer_inv sc1 hoisted to barrier entry (before spin / beside wbl2), 12 seams
# speedup vs baseline: 1.0151x; 1.0151x over previous
.LBB0_147:
	s_or_b64 exec, exec, s[14:15]
	v_cvt_f32_u32_e32 v4, v2
	s_waitcnt vmcnt(0)
	v_readfirstlane_b32 s3, v3
	v_sub_u32_e32 v3, 0, v2
	v_rcp_iflag_f32_e32 v4, v4
	v_add_u32_e32 v5, s3, v1
	v_mul_f32_e32 v4, 0x4f7ffffe, v4
	v_cvt_u32_f32_e32 v4, v4
	v_mul_lo_u32 v1, v3, v4
	v_mul_hi_u32 v1, v4, v1
	v_add_u32_e32 v1, v4, v1
	v_mul_hi_u32 v1, v5, v1
	v_mul_lo_u32 v3, v1, v2
	v_sub_u32_e32 v3, v5, v3
	v_add_u32_e32 v4, 1, v1
	v_cmp_ge_u32_e32 vcc, v3, v2
	s_nop 1
	v_cndmask_b32_e32 v1, v1, v4, vcc
	v_sub_u32_e32 v4, v3, v2
	v_cndmask_b32_e32 v3, v3, v4, vcc
	v_add_u32_e32 v4, 1, v1
	v_cmp_ge_u32_e32 vcc, v3, v2
	v_add_u32_e32 v3, 1, v5
	s_nop 0
	v_cndmask_b32_e32 v1, v1, v4, vcc
	v_mul_lo_u32 v4, v2, v1
	v_add_u32_e32 v2, v4, v2
	v_cmp_ne_u32_e32 vcc, v3, v2
	s_and_saveexec_b64 s[12:13], vcc
	s_xor_b64 s[12:13], exec, s[12:13]
	s_cbranch_execz .LBB0_161
	s_waitcnt lgkmcnt(0)
	buffer_inv sc1
	v_mov_b32_e32 v0, 0x2000
	global_load_dword v0, v0, s[10:11] offset:1024 sc1
	s_add_u32 s16, s10, 0x2400
	s_addc_u32 s17, s11, 0
	s_waitcnt vmcnt(0)
	v_cmp_eq_u32_e32 vcc, v0, v1
	s_and_saveexec_b64 s[14:15], vcc
	s_cbranch_execz .LBB0_160
	s_mov_b32 s3, 1
	s_mov_b64 s[18:19], 0
	v_mov_b32_e32 v0, 0
	s_branch .LBB0_151

.LBB0_160:
	s_or_b64 exec, exec, s[14:15]
	s_waitcnt vmcnt(0)
	s_waitcnt vmcnt(0)
.LBB0_161:
	s_andn2_saveexec_b64 s[12:13], s[12:13]
	s_cbranch_execz .LBB0_181
	s_mov_b64 s[12:13], exec
	buffer_wbl2 sc1
	buffer_inv sc1
	s_waitcnt lgkmcnt(0)
	s_waitcnt vmcnt(0)
	v_mbcnt_lo_u32_b32 v1, s12, 0
	v_mbcnt_hi_u32_b32 v1, s13, v1
	v_cmp_eq_u32_e32 vcc, 0, v1
	s_and_saveexec_b64 s[14:15], vcc
	s_cbranch_execz .LBB0_164
	s_bcnt1_i32_b64 s3, s[12:13]
	v_mov_b32_e32 v2, 0x3000
	v_mov_b32_e32 v3, s3
	global_atomic_add v2, v2, v3, s[42:43] offset:1280 sc0

.LBB0_178:
	s_or_b64 exec, exec, s[12:13]
	s_mov_b64 s[12:13], exec
	v_mbcnt_lo_u32_b32 v0, s12, 0
	v_mbcnt_hi_u32_b32 v0, s13, v0
	v_cmp_eq_u32_e32 vcc, 0, v0
	s_waitcnt vmcnt(0)
	s_and_saveexec_b64 s[14:15], vcc
	s_cbranch_execz .LBB0_180
	s_bcnt1_i32_b64 s3, s[12:13]
	v_mov_b32_e32 v0, 0x2000
	v_mov_b32_e32 v1, s3
	global_atomic_add v0, v1, s[10:11] offset:1024

.LBB0_1453:
	s_or_b64 exec, exec, s[12:13]
	v_cvt_f32_u32_e32 v4, v2
	s_waitcnt vmcnt(0)
	v_readfirstlane_b32 s3, v3
	v_sub_u32_e32 v3, 0, v2
	v_rcp_iflag_f32_e32 v4, v4
	v_add_u32_e32 v5, s3, v1
	v_mul_f32_e32 v4, 0x4f7ffffe, v4
	v_cvt_u32_f32_e32 v4, v4
	v_mul_lo_u32 v1, v3, v4
	v_mul_hi_u32 v1, v4, v1
	v_add_u32_e32 v1, v4, v1
	v_mul_hi_u32 v1, v5, v1
	v_mul_lo_u32 v3, v1, v2
	v_sub_u32_e32 v3, v5, v3
	v_add_u32_e32 v4, 1, v1
	v_cmp_ge_u32_e32 vcc, v3, v2
	s_nop 1
	v_cndmask_b32_e32 v1, v1, v4, vcc
	v_sub_u32_e32 v4, v3, v2
	v_cndmask_b32_e32 v3, v3, v4, vcc
	v_add_u32_e32 v4, 1, v1
	v_cmp_ge_u32_e32 vcc, v3, v2
	v_add_u32_e32 v3, 1, v5
	s_nop 0
	v_cndmask_b32_e32 v1, v1, v4, vcc
	v_mul_lo_u32 v4, v2, v1
	v_add_u32_e32 v2, v4, v2
	v_cmp_ne_u32_e32 vcc, v3, v2
	s_and_saveexec_b64 s[10:11], vcc
	s_xor_b64 s[10:11], exec, s[10:11]
	s_cbranch_execz .LBB0_1467
	s_waitcnt lgkmcnt(0)
	buffer_inv sc1
	v_mov_b32_e32 v0, 0x2000
	global_load_dword v0, v0, s[4:5] offset:1024 sc1
	s_add_u32 s14, s4, 0x2400
	s_addc_u32 s15, s5, 0
	s_waitcnt vmcnt(0)
	v_cmp_eq_u32_e32 vcc, v0, v1
	s_and_saveexec_b64 s[12:13], vcc
	s_cbranch_execz .LBB0_1466
	s_mov_b32 s3, 1
	s_mov_b64 s[16:17], 0
	v_mov_b32_e32 v0, 0
	s_branch .LBB0_1457

.LBB0_1466:
	s_or_b64 exec, exec, s[12:13]
	s_waitcnt vmcnt(0)
	s_waitcnt vmcnt(0)
.LBB0_1467:
	s_andn2_saveexec_b64 s[10:11], s[10:11]
	s_cbranch_execz .LBB0_1487
	s_mov_b64 s[10:11], exec
	buffer_wbl2 sc1
	buffer_inv sc1
	s_waitcnt lgkmcnt(0)
	s_waitcnt vmcnt(0)
	v_mbcnt_lo_u32_b32 v1, s10, 0
	v_mbcnt_hi_u32_b32 v1, s11, v1
	v_cmp_eq_u32_e32 vcc, 0, v1
	s_and_saveexec_b64 s[12:13], vcc
	s_cbranch_execz .LBB0_1470
	s_bcnt1_i32_b64 s3, s[10:11]
	v_mov_b32_e32 v2, 0x3000
	v_mov_b32_e32 v3, s3
	global_atomic_add v2, v2, v3, s[42:43] offset:1280 sc0

.LBB0_1484:
	s_or_b64 exec, exec, s[10:11]
	s_mov_b64 s[10:11], exec
	v_mbcnt_lo_u32_b32 v0, s10, 0
	v_mbcnt_hi_u32_b32 v0, s11, v0
	v_cmp_eq_u32_e32 vcc, 0, v0
	s_waitcnt vmcnt(0)
	s_and_saveexec_b64 s[12:13], vcc
	s_cbranch_execz .LBB0_1486
	s_bcnt1_i32_b64 s3, s[10:11]
	v_mov_b32_e32 v0, 0x2000
	v_mov_b32_e32 v1, s3
	global_atomic_add v0, v1, s[4:5] offset:1024
